# attention: sum-guard softmax (no max reduction on the fast path; exact power-of-two re-reference / recompute fallbacks), redo-once flag
# baseline (speedup 1.0000x reference)
; #define LAS __attribute__((address_space(3)))
; #define wave (__builtin_amdgcn_readfirstlane((int)(threadIdx.x >> 6)))
; __device__ __forceinline__ void attn_phase(LAS unsigned char* lds, const bf16_t* __restrict__ Q, const bf16_t* __restrict__ KN, const bf16_t* __restrict__ KR,
;                                            const bf16_t* __restrict__ VT, bf16_t* AO, int vcu, int G, int tid, int lane, int wave) {
;     ...
;             const int bh = p >> 3, pp = p & 7, qb = half ? 15 - pp : pp, b = bh >> 3, h = bh & 7;
;             const size_t rowbase = (size_t)b * SEQ;
;             const int qrow0 = qb * 256 + wave * 32, qc = qrow0 >> 6, NT2 = 2 * qb + 2;
;             bf16x8 qf[6];
;             { const bf16_t* qp = Q + (rowbase + qrow0 + r32) * NQ + h * 96 + 8 * hi;
; #pragma unroll
;               for (int ks = 0; ks < 6; ++ks) qf[ks] = *(const bf16x8*)(qp + 16 * ks); }
;             const char* kbase = (const char*)(KN + rowbase * NKN + h * 64); const unsigned koff = (unsigned)(key_l * NKN + 8 * kc) * 2u;
;             const char* rbase = (const char*)(KR + rowbase * 32); const unsigned roff = (unsigned)(key_r * 32 + 8 * rc) * 2u;
;             const char* vbase = (const char*)(VT + (size_t)(h * 64) * MTOK + rowbase); const unsigned voff = (unsigned)((size_t)vd * MTOK + 8 * vc) * 2u;
;             const int kdst = (key_l * KP + 8 * kc) * 2, rdst = (key_r * KP + 64 + 8 * rc) * 2, vdst = KBUF + (vd * VP + 8 * vc) * 2;
;             u32x4 gk0, gk1, gr, gv0, gv1;
;             gk0 = *(const u32x4*)(kbase + koff); gk1 = *(const u32x4*)(kbase + 64 * NKN * 2 + koff); gr = *(const u32x4*)(rbase + roff); gv0 = *(const u32x4*)(vbase + voff); gv1 = *(const u32x4*)(vbase + 128 + voff);
;             *(LAS u32x4*)(lds + kdst) = gk0; *(LAS u32x4*)(lds + kdst + 64 * KP * 2) = gk1; *(LAS u32x4*)(lds + rdst) = gr; *(LAS u32x4*)(lds + vdst) = gv0; *(LAS u32x4*)(lds + vdst + 128) = gv1;
;             __syncthreads();
;             float m_run = -INFINITY, l_run = 0.f;
;             f32x16 o0, o1;
; #pragma unroll
;             for (int r = 0; r < 16; ++r) { o0[r] = 0.f; o1[r] = 0.f; }
.LBB0_533:
	s_xor_b64 s[12:13], s[6:7], -1
	s_and_b64 s[6:7], s[6:7], exec
	s_cselect_b32 s14, s23, s31
	s_lshl_b32 s6, s14, 8
	s_add_i32 s8, s6, s20
	v_lshl_add_u64 v[216:217], v[212:213], 0, s[8:9]
	s_lshl_b32 s36, s14, 1
	global_load_dwordx4 v[228:231], v198, s[10:11]
	s_add_u32 s14, s10, 0x10000
	s_addc_u32 s15, s11, 0
	v_mad_u64_u32 v[250:251], s[6:7], v216, s21, v[206:207]
	global_load_dwordx4 v[232:235], v198, s[14:15]
	v_mad_i32_i24 v251, v217, s21, v251
	global_load_dwordx4 v[236:239], v[208:209], off
	global_load_dwordx4 v[240:243], v[210:211], off
	global_load_dwordx4 v[244:247], v[210:211], off offset:128
	global_load_dwordx4 v[114:117], v[250:251], off
	global_load_dwordx4 v[118:121], v[250:251], off offset:32
	global_load_dwordx4 v[122:125], v[250:251], off offset:64
	global_load_dwordx4 v[126:129], v[250:251], off offset:96
	global_load_dwordx4 v[130:133], v[250:251], off offset:128
	global_load_dwordx4 v[134:137], v[250:251], off offset:160
	v_mov_b32_e32 v2, 0
	v_mov_b32_e32 v3, 0
	v_mov_b32_e32 v4, 0
	v_mov_b32_e32 v5, 0
	v_mov_b32_e32 v6, 0
	v_mov_b32_e32 v7, 0
	v_mov_b32_e32 v8, 0
	v_mov_b32_e32 v9, 0
	v_mov_b32_e32 v10, 0
	v_mov_b32_e32 v11, 0
	v_mov_b32_e32 v12, 0
	v_mov_b32_e32 v13, 0
	v_mov_b32_e32 v14, 0
	v_mov_b32_e32 v15, 0
	v_mov_b32_e32 v16, 0
	v_mov_b32_e32 v17, 0
	v_mov_b32_e32 v18, 0
	v_mov_b32_e32 v19, 0
	v_mov_b32_e32 v20, 0
	v_mov_b32_e32 v21, 0
	v_mov_b32_e32 v22, 0
	v_mov_b32_e32 v23, 0
	v_mov_b32_e32 v24, 0
	v_mov_b32_e32 v25, 0
	v_mov_b32_e32 v26, 0
	v_mov_b32_e32 v27, 0
	v_mov_b32_e32 v28, 0
	v_mov_b32_e32 v29, 0
	v_mov_b32_e32 v30, 0
	v_mov_b32_e32 v31, 0
	v_mov_b32_e32 v32, 0
	v_mov_b32_e32 v33, 0
	v_mov_b32_e32 v98, 0
	v_mov_b32_e32 v99, 0
	v_mov_b32_e32 v100, 0
	v_mov_b32_e32 v101, 0
	v_mov_b32_e32 v102, 0
	v_mov_b32_e32 v103, 0
	v_mov_b32_e32 v104, 0
	v_mov_b32_e32 v105, 0
	v_mov_b32_e32 v106, 0
	v_mov_b32_e32 v107, 0
	v_mov_b32_e32 v108, 0
	v_mov_b32_e32 v109, 0
	v_mov_b32_e32 v110, 0
	v_mov_b32_e32 v111, 0
	v_mov_b32_e32 v112, 0
	v_mov_b32_e32 v113, 0
	v_mov_b32_e32 v227, 0
	v_mov_b32_e32 v248, 0
	s_add_i32 s36, s36, 2
	s_lshr_b32 s33, s8, 6
	s_mov_b32 s8, 0
	s_mov_b32 s26, 0x4e800000
	s_mov_b32 s27, 0xff7fffff
	s_mov_b32 s6, 0
	s_mov_b32 s7, 1
	v_mov_b32_e32 v218, 0
	s_waitcnt vmcnt(6)
	s_mov_b32 s38, 0
	v_add_u32_e32 v1, s38, v219
	ds_write_b128 v1, v[228:231]
	ds_write_b128 v1, v[232:235] offset:13312
	v_add_u32_e32 v1, s38, v220
	ds_write_b128 v1, v[236:239]
	v_add_u32_e32 v1, s38, v221
	ds_write_b128 v1, v[240:243] offset:26624
	ds_write_b128 v1, v[244:247] offset:26752
	s_waitcnt lgkmcnt(0)
	s_barrier

; #define LAS __attribute__((address_space(3)))
; __device__ __forceinline__ void attn_phase(LAS unsigned char* lds, const bf16_t* __restrict__ Q, const bf16_t* __restrict__ KN, const bf16_t* __restrict__ KR,
;                                            const bf16_t* __restrict__ VT, bf16_t* AO, int vcu, int G, int tid, int lane, int wave) {
;     ...
;                 const LAS unsigned char* kA = buf + (pr * KP + 8 * hi) * 2; const LAS unsigned char* vA = buf + KBUF + (r32 * VP + 8 * hi) * 2;
;                 if (2 * t + 1 <= qc) {
;                     bf16x8 kf[12], kf2[12], vf[8], vf2[8], pa[4], pb2[4]; f32x16 a0, a1, b0, b1;
;                     attn_ldk(kf, kA);
;                     __builtin_amdgcn_sched_barrier(0);
;                     attn_qk(a0, a1, kf, qf);
;                     attn_ldk(kf2, kA + 64 * KP * 2);
;                     __builtin_amdgcn_sched_barrier(0);
;                     attn_qk(b0, b1, kf2, qf);
.Lat_both:
	v_add_u32_e32 v1, s37, v222
	v_add_u32_e32 v225, s37, v223
	ds_read_b128 v[138:141], v1
	ds_read_b128 v[142:145], v1 offset:6656
	ds_read_b128 v[146:149], v1 offset:32
	ds_read_b128 v[150:153], v1 offset:6688
	ds_read_b128 v[154:157], v1 offset:64
	ds_read_b128 v[158:161], v1 offset:6720
	ds_read_b128 v[162:165], v1 offset:96
	ds_read_b128 v[166:169], v1 offset:6752
	s_waitcnt vmcnt(5)
	s_waitcnt lgkmcnt(7)
	v_mfma_f32_32x32x16_bf16 v[34:49], v[138:141], v[114:117], v[98:113]
	ds_read_b128 v[138:141], v1 offset:128
	s_waitcnt lgkmcnt(7)
	v_mfma_f32_32x32x16_bf16 v[50:65], v[142:145], v[114:117], v[98:113]
	ds_read_b128 v[142:145], v1 offset:6784
	s_waitcnt lgkmcnt(7)
	v_mfma_f32_32x32x16_bf16 v[34:49], v[146:149], v[118:121], v[34:49]
	ds_read_b128 v[146:149], v1 offset:160
	s_waitcnt lgkmcnt(7)
	v_mfma_f32_32x32x16_bf16 v[50:65], v[150:153], v[118:121], v[50:65]
	ds_read_b128 v[150:153], v1 offset:6816
	s_waitcnt lgkmcnt(7)
	v_mfma_f32_32x32x16_bf16 v[34:49], v[154:157], v[122:125], v[34:49]
	ds_read_b128 v[154:157], v1 offset:13312
	s_waitcnt lgkmcnt(7)
	v_mfma_f32_32x32x16_bf16 v[50:65], v[158:161], v[122:125], v[50:65]
	ds_read_b128 v[158:161], v1 offset:19968
	s_waitcnt lgkmcnt(7)
	v_mfma_f32_32x32x16_bf16 v[34:49], v[162:165], v[126:129], v[34:49]
	ds_read_b128 v[162:165], v1 offset:13344
	s_waitcnt lgkmcnt(7)
	v_mfma_f32_32x32x16_bf16 v[50:65], v[166:169], v[126:129], v[50:65]
	ds_read_b128 v[166:169], v1 offset:20000
	s_waitcnt lgkmcnt(7)
	v_mfma_f32_32x32x16_bf16 v[34:49], v[138:141], v[130:133], v[34:49]
	ds_read_b128 v[138:141], v1 offset:13376
	s_waitcnt lgkmcnt(7)
	v_mfma_f32_32x32x16_bf16 v[50:65], v[142:145], v[130:133], v[50:65]
	ds_read_b128 v[142:145], v1 offset:20032
	s_waitcnt lgkmcnt(7)
	v_mfma_f32_32x32x16_bf16 v[34:49], v[146:149], v[134:137], v[34:49]
	ds_read_b128 v[146:149], v1 offset:13408
	s_waitcnt lgkmcnt(7)
	v_mfma_f32_32x32x16_bf16 v[50:65], v[150:153], v[134:137], v[50:65]
	ds_read_b128 v[150:153], v1 offset:20064
	s_waitcnt lgkmcnt(7)
	v_mfma_f32_32x32x16_bf16 v[66:81], v[154:157], v[114:117], v[98:113]
	ds_read_b128 v[154:157], v1 offset:13440
	s_waitcnt lgkmcnt(7)
	v_mfma_f32_32x32x16_bf16 v[82:97], v[158:161], v[114:117], v[98:113]
	ds_read_b128 v[158:161], v1 offset:20096
	s_waitcnt lgkmcnt(7)
	v_mfma_f32_32x32x16_bf16 v[66:81], v[162:165], v[118:121], v[66:81]
	ds_read_b128 v[162:165], v1 offset:13472
	s_waitcnt lgkmcnt(7)
	v_mfma_f32_32x32x16_bf16 v[82:97], v[166:169], v[118:121], v[82:97]
	ds_read_b128 v[166:169], v1 offset:20128
	s_waitcnt lgkmcnt(7)
	v_mfma_f32_32x32x16_bf16 v[66:81], v[138:141], v[122:125], v[66:81]
	ds_read_b128 v[170:173], v225 offset:26624
	s_waitcnt lgkmcnt(7)
	v_mfma_f32_32x32x16_bf16 v[82:97], v[142:145], v[122:125], v[82:97]
	ds_read_b128 v[174:177], v225 offset:35328
	s_waitcnt lgkmcnt(7)
	v_mfma_f32_32x32x16_bf16 v[66:81], v[146:149], v[126:129], v[66:81]
	ds_read_b128 v[178:181], v225 offset:26656
	s_waitcnt lgkmcnt(7)
	v_mfma_f32_32x32x16_bf16 v[82:97], v[150:153], v[126:129], v[82:97]
	ds_read_b128 v[182:185], v225 offset:35360
	s_waitcnt lgkmcnt(7)
	v_mfma_f32_32x32x16_bf16 v[66:81], v[154:157], v[130:133], v[66:81]
	ds_read_b128 v[186:189], v225 offset:26688
	s_waitcnt lgkmcnt(7)
	v_mfma_f32_32x32x16_bf16 v[82:97], v[158:161], v[130:133], v[82:97]
	ds_read_b128 v[190:193], v225 offset:35392
	s_waitcnt lgkmcnt(7)
	v_mfma_f32_32x32x16_bf16 v[66:81], v[162:165], v[134:137], v[66:81]
	s_waitcnt lgkmcnt(6)
	v_mfma_f32_32x32x16_bf16 v[82:97], v[166:169], v[134:137], v[82:97]
	s_mov_b32 s41, 0
	s_cmp_lg_u32 s7, 0
	s_cbranch_scc1 .Lat_first_A2

; __device__ __forceinline__ void attn_phase(LAS unsigned char* lds, const bf16_t* __restrict__ Q, const bf16_t* __restrict__ KN, const bf16_t* __restrict__ KR,
;                                            const bf16_t* __restrict__ VT, bf16_t* AO, int vcu, int G, int tid, int lane, int wave) {
;     ...
;                     attn_softmax(a0, a1, pa, o0, o1, m_run, l_run);
;                     attn_ldv(vf, vA);
;                     __builtin_amdgcn_sched_barrier(0);
;                     PREFETCH_NEXT();
;                     attn_ldv(vf2, vA + 128);
;                     __builtin_amdgcn_sched_barrier(0);
;                     attn_pv(vf, pa, o0, o1);
;                     attn_softmax(b0, b1, pb2, o0, o1, m_run, l_run);
.Lat_fixed_B:
	s_mov_b32 s41, 0
	s_cmp_lg_u32 s7, 0
	s_cbranch_scc1 .Lat_first_B2

; __device__ __forceinline__ void attn_phase(LAS unsigned char* lds, const bf16_t* __restrict__ Q, const bf16_t* __restrict__ KN, const bf16_t* __restrict__ KR,
;                                            const bf16_t* __restrict__ VT, bf16_t* AO, int vcu, int G, int tid, int lane, int wave) {
;     ...
;                 } else if (2 * t <= qc) {
;                     bf16x8 kf[12], vf[8], pa[4]; f32x16 a0, a1;
;                     PREFETCH_NEXT();
;                     attn_ldk(kf, kA);
;                     __builtin_amdgcn_sched_barrier(0);
;                     attn_qk(a0, a1, kf, qf);
;                     __builtin_amdgcn_sched_barrier(0);
;                     attn_ldv(vf, vA);
;                     __builtin_amdgcn_sched_barrier(0);
;                     attn_softmax(a0, a1, pa, o0, o1, m_run, l_run);
.Lat_single:
	v_add_u32_e32 v1, s37, v222
	v_add_u32_e32 v225, s37, v223
	ds_read_b128 v[138:141], v1
	ds_read_b128 v[142:145], v1 offset:6656
	ds_read_b128 v[146:149], v1 offset:32
	ds_read_b128 v[150:153], v1 offset:6688
	ds_read_b128 v[154:157], v1 offset:64
	ds_read_b128 v[158:161], v1 offset:6720
	ds_read_b128 v[162:165], v1 offset:96
	ds_read_b128 v[166:169], v1 offset:6752
	s_waitcnt vmcnt(5)
	s_waitcnt lgkmcnt(7)
	v_mfma_f32_32x32x16_bf16 v[34:49], v[138:141], v[114:117], v[98:113]
	ds_read_b128 v[138:141], v1 offset:128
	s_waitcnt lgkmcnt(7)
	v_mfma_f32_32x32x16_bf16 v[50:65], v[142:145], v[114:117], v[98:113]
	ds_read_b128 v[142:145], v1 offset:6784
	s_waitcnt lgkmcnt(7)
	v_mfma_f32_32x32x16_bf16 v[34:49], v[146:149], v[118:121], v[34:49]
	ds_read_b128 v[146:149], v1 offset:160
	s_waitcnt lgkmcnt(7)
	v_mfma_f32_32x32x16_bf16 v[50:65], v[150:153], v[118:121], v[50:65]
	ds_read_b128 v[150:153], v1 offset:6816
	s_waitcnt lgkmcnt(7)
	v_mfma_f32_32x32x16_bf16 v[34:49], v[154:157], v[122:125], v[34:49]
	ds_read_b128 v[170:173], v225 offset:26624
	s_waitcnt lgkmcnt(7)
	v_mfma_f32_32x32x16_bf16 v[50:65], v[158:161], v[122:125], v[50:65]
	ds_read_b128 v[174:177], v225 offset:35328
	s_waitcnt lgkmcnt(7)
	v_mfma_f32_32x32x16_bf16 v[34:49], v[162:165], v[126:129], v[34:49]
	ds_read_b128 v[178:181], v225 offset:26656
	s_waitcnt lgkmcnt(7)
	v_mfma_f32_32x32x16_bf16 v[50:65], v[166:169], v[126:129], v[50:65]
	ds_read_b128 v[182:185], v225 offset:35360
	s_waitcnt lgkmcnt(7)
	v_mfma_f32_32x32x16_bf16 v[34:49], v[138:141], v[130:133], v[34:49]
	ds_read_b128 v[186:189], v225 offset:26688
	s_waitcnt lgkmcnt(7)
	v_mfma_f32_32x32x16_bf16 v[50:65], v[142:145], v[130:133], v[50:65]
	ds_read_b128 v[190:193], v225 offset:35392
	s_waitcnt lgkmcnt(7)
	v_mfma_f32_32x32x16_bf16 v[34:49], v[146:149], v[134:137], v[34:49]
	s_waitcnt lgkmcnt(6)
	v_mfma_f32_32x32x16_bf16 v[50:65], v[150:153], v[134:137], v[50:65]
	s_mov_b32 s41, 0
	s_cmp_lg_u32 s7, 0
	s_cbranch_scc1 .Lat_first_A1
.Lat_exp_A1:
	s_nop 6
	v_exp_f32_e32 v34, v34
	s_nop 0
	v_exp_f32_e32 v50, v50
	v_exp_f32_e32 v35, v35
	v_exp_f32_e32 v51, v51
	v_exp_f32_e32 v36, v36
	v_exp_f32_e32 v52, v52
	v_exp_f32_e32 v37, v37
	v_exp_f32_e32 v53, v53
	v_exp_f32_e32 v38, v38
	v_exp_f32_e32 v54, v54
	v_exp_f32_e32 v39, v39
	v_exp_f32_e32 v55, v55
	v_exp_f32_e32 v40, v40
	v_exp_f32_e32 v56, v56
	v_exp_f32_e32 v41, v41
	v_exp_f32_e32 v57, v57
	v_exp_f32_e32 v42, v42
	v_exp_f32_e32 v58, v58
	v_exp_f32_e32 v43, v43
	v_exp_f32_e32 v59, v59
	v_exp_f32_e32 v44, v44
	v_exp_f32_e32 v60, v60
	v_exp_f32_e32 v45, v45
	v_exp_f32_e32 v61, v61
	v_exp_f32_e32 v46, v46
	v_exp_f32_e32 v62, v62
	v_exp_f32_e32 v47, v47
	v_exp_f32_e32 v63, v63
	v_exp_f32_e32 v48, v48
	v_exp_f32_e32 v64, v64
	v_exp_f32_e32 v49, v49
	v_exp_f32_e32 v65, v65
	v_pk_add_f32 v[250:251], v[34:35], v[36:37]
	v_pk_add_f32 v[252:253], v[50:51], v[52:53]
	v_pk_add_f32 v[250:251], v[250:251], v[38:39]
	v_pk_add_f32 v[252:253], v[252:253], v[54:55]
	v_pk_add_f32 v[250:251], v[250:251], v[40:41]
	v_pk_add_f32 v[252:253], v[252:253], v[56:57]
	v_pk_add_f32 v[250:251], v[250:251], v[42:43]
	v_pk_add_f32 v[252:253], v[252:253], v[58:59]
	v_pk_add_f32 v[250:251], v[250:251], v[44:45]
	v_pk_add_f32 v[252:253], v[252:253], v[60:61]
	v_pk_add_f32 v[250:251], v[250:251], v[46:47]
	v_pk_add_f32 v[252:253], v[252:253], v[62:63]
	v_pk_add_f32 v[250:251], v[250:251], v[48:49]
	v_pk_add_f32 v[252:253], v[252:253], v[64:65]
	v_pk_add_f32 v[250:251], v[250:251], v[252:253]
	v_add_f32_e32 v1, v250, v251
	v_cmp_lt_f32_e32 vcc, s26, v1
	s_cbranch_vccnz .Lat_rare_A1

; __device__ __forceinline__ float max3f(float a, float b, float c) { return fmaxf(fmaxf(a, b), c); }
; __device__ __forceinline__ void attn_softmax(f32x16& p0, f32x16& p1, bf16x8 (&pb)[4], f32x16& o0, f32x16& o1, float& m_run, float& l_run) {
;     float mx = max3f(p0[0], p0[1], p1[0]), my = max3f(p0[2], p0[3], p1[1]);
;     mx = max3f(mx, p1[2], p1[3]);
; #pragma unroll
;     for (int r = 4; r < 16; r += 4) { mx = max3f(mx, p0[r], p0[r + 1]); my = max3f(my, p0[r + 2], p0[r + 3]); mx = max3f(mx, p1[r], p1[r + 1]); my = max3f(my, p1[r + 2], p1[r + 3]); }
;     mx = fmaxf(mx, my);
;     { auto rr = __builtin_amdgcn_permlane32_swap(__float_as_uint(mx), __float_as_uint(mx), false, false); mx = fmaxf(__uint_as_float(rr[0]), __uint_as_float(rr[1])); }
;     const float m_new = fmaxf(m_run, mx);
;     const float alpha = __builtin_amdgcn_exp2f(m_run - m_new);
;     m_run = m_new;
;     p0 = p0 - m_new; p1 = p1 - m_new;
; #pragma unroll
;     for (int r = 0; r < 16; ++r) { p0[r] = __builtin_amdgcn_exp2f(p0[r]); p1[r] = __builtin_amdgcn_exp2f(p1[r]); }
;     f32x16 sm = p0 + p1;
;     f32x2v s2 = (f32x2v){sm[0], sm[1]} + (f32x2v){sm[2], sm[3]};
; #pragma unroll
;     for (int r = 4; r < 16; r += 2) s2 += (f32x2v){sm[r], sm[r + 1]};
;     l_run = l_run * alpha + (s2[0] + s2[1]);
;     o0 = o0 * alpha; o1 = o1 * alpha;
.Lat_first_A2:
	s_nop 15
	v_max3_f32 v249, v34, v35, v36
	v_max3_f32 v1, v50, v51, v52
	v_max3_f32 v249, v249, v37, v38
	v_max3_f32 v1, v1, v53, v54
	v_max3_f32 v249, v249, v39, v40
	v_max3_f32 v1, v1, v55, v56
	v_max3_f32 v249, v249, v41, v42
	v_max3_f32 v1, v1, v57, v58
	v_max3_f32 v249, v249, v43, v44
	v_max3_f32 v1, v1, v59, v60
	v_max3_f32 v249, v249, v45, v46
	v_max3_f32 v1, v1, v61, v62
	v_max3_f32 v249, v249, v47, v48
	v_max3_f32 v1, v1, v63, v64
	v_max_f32_e32 v249, v249, v49
	v_max_f32_e32 v1, v1, v65
	v_max_f32_e32 v249, v249, v1
	v_mov_b32_e32 v1, v249
	s_nop 1
	v_permlane32_swap_b32_e32 v249, v1
	v_max_f32_e32 v249, v249, v1
	v_max_f32_e32 v250, s27, v249
	v_add_f32_e32 v248, v248, v250
	v_sub_f32_e32 v251, 0, v248
	v_mov_b32_e32 v98, v251
	v_mov_b32_e32 v99, v251
	v_mov_b32_e32 v100, v251
	v_mov_b32_e32 v101, v251
	v_mov_b32_e32 v102, v251
	v_mov_b32_e32 v103, v251
	v_mov_b32_e32 v104, v251
	v_mov_b32_e32 v105, v251
	v_mov_b32_e32 v106, v251
	v_mov_b32_e32 v107, v251
	v_mov_b32_e32 v108, v251
	v_mov_b32_e32 v109, v251
	v_mov_b32_e32 v110, v251
	v_mov_b32_e32 v111, v251
	v_mov_b32_e32 v112, v251
	v_mov_b32_e32 v113, v251
	v_sub_f32_e32 v34, v34, v250
	v_sub_f32_e32 v35, v35, v250
	v_sub_f32_e32 v36, v36, v250
	v_sub_f32_e32 v37, v37, v250
	v_sub_f32_e32 v38, v38, v250
	v_sub_f32_e32 v39, v39, v250
	v_sub_f32_e32 v40, v40, v250
	v_sub_f32_e32 v41, v41, v250
	v_sub_f32_e32 v42, v42, v250
	v_sub_f32_e32 v43, v43, v250
	v_sub_f32_e32 v44, v44, v250
	v_sub_f32_e32 v45, v45, v250
	v_sub_f32_e32 v46, v46, v250
	v_sub_f32_e32 v47, v47, v250
	v_sub_f32_e32 v48, v48, v250
	v_sub_f32_e32 v49, v49, v250
	v_sub_f32_e32 v50, v50, v250
	v_sub_f32_e32 v51, v51, v250
	v_sub_f32_e32 v52, v52, v250
	v_sub_f32_e32 v53, v53, v250
	v_sub_f32_e32 v54, v54, v250
	v_sub_f32_e32 v55, v55, v250
	v_sub_f32_e32 v56, v56, v250
	v_sub_f32_e32 v57, v57, v250
	v_sub_f32_e32 v58, v58, v250
	v_sub_f32_e32 v59, v59, v250
	v_sub_f32_e32 v60, v60, v250
	v_sub_f32_e32 v61, v61, v250
	v_sub_f32_e32 v62, v62, v250
	v_sub_f32_e32 v63, v63, v250
	v_sub_f32_e32 v64, v64, v250
	v_sub_f32_e32 v65, v65, v250
	v_sub_f32_e32 v252, 0, v250
	v_min_f32_e32 v252, 0x42800000, v252
	v_exp_f32_e32 v252, v252
	s_mov_b32 s7, 0
	s_mov_b32 s27, 0
	v_mul_f32_e32 v227, v227, v252
	v_mul_f32_e32 v2, v2, v252
	v_mul_f32_e32 v3, v3, v252
	v_mul_f32_e32 v4, v4, v252
	v_mul_f32_e32 v5, v5, v252
	v_mul_f32_e32 v6, v6, v252
	v_mul_f32_e32 v7, v7, v252
	v_mul_f32_e32 v8, v8, v252
	v_mul_f32_e32 v9, v9, v252
	v_mul_f32_e32 v10, v10, v252
	v_mul_f32_e32 v11, v11, v252
	v_mul_f32_e32 v12, v12, v252
	v_mul_f32_e32 v13, v13, v252
	v_mul_f32_e32 v14, v14, v252
	v_mul_f32_e32 v15, v15, v252
	v_mul_f32_e32 v16, v16, v252
	v_mul_f32_e32 v17, v17, v252
	v_mul_f32_e32 v18, v18, v252
	v_mul_f32_e32 v19, v19, v252
	v_mul_f32_e32 v20, v20, v252
	v_mul_f32_e32 v21, v21, v252
	v_mul_f32_e32 v22, v22, v252
	v_mul_f32_e32 v23, v23, v252
	v_mul_f32_e32 v24, v24, v252
	v_mul_f32_e32 v25, v25, v252
	v_mul_f32_e32 v26, v26, v252
	v_mul_f32_e32 v27, v27, v252
	v_mul_f32_e32 v28, v28, v252
	v_mul_f32_e32 v29, v29, v252
	v_mul_f32_e32 v30, v30, v252
	v_mul_f32_e32 v31, v31, v252
	v_mul_f32_e32 v32, v32, v252
	v_mul_f32_e32 v33, v33, v252
	v_add_f32_e32 v218, v218, v250
	s_mov_b32 s6, 1
	s_nop 1
	s_branch .Lat_exp_A2
.Lat_rare_A2:
	s_nop 15
	s_cmp_lg_u32 s41, 0
	s_cbranch_scc1 .Lat_resc_A2
	v_cmp_lt_f32_e32 vcc, 0x71800000, v1
	s_cbranch_vccnz .Lat_redo_A2
; __device__ __forceinline__ float max3f(float a, float b, float c) { return fmaxf(fmaxf(a, b), c); }
; __device__ __forceinline__ void attn_qk(f32x16& p0, f32x16& p1, const bf16x8 (&kf)[12], const bf16x8 (&qf)[6]) {
;     const f32x16 zero = {0.f, 0.f, 0.f, 0.f, 0.f, 0.f, 0.f, 0.f, 0.f, 0.f, 0.f, 0.f, 0.f, 0.f, 0.f, 0.f};
; #pragma unroll
;     for (int ks = 0; ks < 6; ++ks) {
;         p0 = __builtin_amdgcn_mfma_f32_32x32x16_bf16(kf[2 * ks], qf[ks], ks == 0 ? zero : p0, 0, 0, 0);
;         p1 = __builtin_amdgcn_mfma_f32_32x32x16_bf16(kf[2 * ks + 1], qf[ks], ks == 0 ? zero : p1, 0, 0, 0);
;     }
; __device__ __forceinline__ void attn_softmax(f32x16& p0, f32x16& p1, bf16x8 (&pb)[4], f32x16& o0, f32x16& o1, float& m_run, float& l_run) {
;     float mx = max3f(p0[0], p0[1], p1[0]), my = max3f(p0[2], p0[3], p1[1]);
;     mx = max3f(mx, p1[2], p1[3]);
; #pragma unroll
;     for (int r = 4; r < 16; r += 4) { mx = max3f(mx, p0[r], p0[r + 1]); my = max3f(my, p0[r + 2], p0[r + 3]); mx = max3f(mx, p1[r], p1[r + 1]); my = max3f(my, p1[r + 2], p1[r + 3]); }
;     mx = fmaxf(mx, my);
;     { auto rr = __builtin_amdgcn_permlane32_swap(__float_as_uint(mx), __float_as_uint(mx), false, false); mx = fmaxf(__uint_as_float(rr[0]), __uint_as_float(rr[1])); }
;     const float m_new = fmaxf(m_run, mx);
;     const float alpha = __builtin_amdgcn_exp2f(m_run - m_new);
;     m_run = m_new;
;     p0 = p0 - m_new; p1 = p1 - m_new;
; #pragma unroll
;     for (int r = 0; r < 16; ++r) { p0[r] = __builtin_amdgcn_exp2f(p0[r]); p1[r] = __builtin_amdgcn_exp2f(p1[r]); }
;     f32x16 sm = p0 + p1;
;     f32x2v s2 = (f32x2v){sm[0], sm[1]} + (f32x2v){sm[2], sm[3]};
; #pragma unroll
;     for (int r = 4; r < 16; r += 2) s2 += (f32x2v){sm[r], sm[r + 1]};
;     l_run = l_run * alpha + (s2[0] + s2[1]);
;     o0 = o0 * alpha; o1 = o1 * alpha;
.Lat_resc_A2:
	v_frexp_exp_i32_f32_e32 v250, v1
	v_max_i32_e32 v250, 0, v250
	v_mov_b32_e32 v251, v250
	s_nop 1
	v_permlane32_swap_b32_e32 v250, v251
	v_max_i32_e32 v250, v250, v251
	v_sub_u32_e32 v251, 0, v250
	v_ldexp_f32 v34, v34, v251
	v_ldexp_f32 v35, v35, v251
	v_ldexp_f32 v36, v36, v251
	v_ldexp_f32 v37, v37, v251
	v_ldexp_f32 v38, v38, v251
	v_ldexp_f32 v39, v39, v251
	v_ldexp_f32 v40, v40, v251
	v_ldexp_f32 v41, v41, v251
	v_ldexp_f32 v42, v42, v251
	v_ldexp_f32 v43, v43, v251
	v_ldexp_f32 v44, v44, v251
	v_ldexp_f32 v45, v45, v251
	v_ldexp_f32 v46, v46, v251
	v_ldexp_f32 v47, v47, v251
	v_ldexp_f32 v48, v48, v251
	v_ldexp_f32 v49, v49, v251
	v_ldexp_f32 v50, v50, v251
	v_ldexp_f32 v51, v51, v251
	v_ldexp_f32 v52, v52, v251
	v_ldexp_f32 v53, v53, v251
	v_ldexp_f32 v54, v54, v251
	v_ldexp_f32 v55, v55, v251
	v_ldexp_f32 v56, v56, v251
	v_ldexp_f32 v57, v57, v251
	v_ldexp_f32 v58, v58, v251
	v_ldexp_f32 v59, v59, v251
	v_ldexp_f32 v60, v60, v251
	v_ldexp_f32 v61, v61, v251
	v_ldexp_f32 v62, v62, v251
	v_ldexp_f32 v63, v63, v251
	v_ldexp_f32 v64, v64, v251
	v_ldexp_f32 v65, v65, v251
	v_ldexp_f32 v1, v1, v251
	v_ldexp_f32 v227, v227, v251
	v_ldexp_f32 v2, v2, v251
	v_ldexp_f32 v3, v3, v251
	v_ldexp_f32 v4, v4, v251
	v_ldexp_f32 v5, v5, v251
	v_ldexp_f32 v6, v6, v251
	v_ldexp_f32 v7, v7, v251
	v_ldexp_f32 v8, v8, v251
	v_ldexp_f32 v9, v9, v251
	v_ldexp_f32 v10, v10, v251
	v_ldexp_f32 v11, v11, v251
	v_ldexp_f32 v12, v12, v251
	v_ldexp_f32 v13, v13, v251
	v_ldexp_f32 v14, v14, v251
	v_ldexp_f32 v15, v15, v251
	v_ldexp_f32 v16, v16, v251
	v_ldexp_f32 v17, v17, v251
	v_ldexp_f32 v18, v18, v251
	v_ldexp_f32 v19, v19, v251
	v_ldexp_f32 v20, v20, v251
	v_ldexp_f32 v21, v21, v251
	v_ldexp_f32 v22, v22, v251
	v_ldexp_f32 v23, v23, v251
	v_ldexp_f32 v24, v24, v251
	v_ldexp_f32 v25, v25, v251
	v_ldexp_f32 v26, v26, v251
	v_ldexp_f32 v27, v27, v251
	v_ldexp_f32 v28, v28, v251
	v_ldexp_f32 v29, v29, v251
	v_ldexp_f32 v30, v30, v251
	v_ldexp_f32 v31, v31, v251
	v_ldexp_f32 v32, v32, v251
	v_ldexp_f32 v33, v33, v251
	v_cvt_f32_i32_e32 v252, v250
	v_add_f32_e32 v248, v248, v252
	v_sub_f32_e32 v253, 0, v248
	v_mov_b32_e32 v98, v253
	v_mov_b32_e32 v99, v253
	v_mov_b32_e32 v100, v253
	v_mov_b32_e32 v101, v253
	v_mov_b32_e32 v102, v253
	v_mov_b32_e32 v103, v253
	v_mov_b32_e32 v104, v253
	v_mov_b32_e32 v105, v253
	v_mov_b32_e32 v106, v253
	v_mov_b32_e32 v107, v253
	v_mov_b32_e32 v108, v253
	v_mov_b32_e32 v109, v253
	v_mov_b32_e32 v110, v253
	v_mov_b32_e32 v111, v253
	v_mov_b32_e32 v112, v253
	v_mov_b32_e32 v113, v253
	v_add_f32_e32 v218, v218, v252
	s_mov_b32 s6, 1
	s_nop 1
	s_branch .Lat_fast_A2
.Lat_redo_A2:
	s_nop 15
	s_mov_b32 s41, 1
	v_add_u32_e32 v1, s37, v222
	ds_read_b128 v[138:141], v1
	ds_read_b128 v[142:145], v1 offset:6656
	ds_read_b128 v[146:149], v1 offset:32
	ds_read_b128 v[150:153], v1 offset:6688
	ds_read_b128 v[154:157], v1 offset:64
	ds_read_b128 v[158:161], v1 offset:6720
	ds_read_b128 v[162:165], v1 offset:96
	ds_read_b128 v[166:169], v1 offset:6752
	s_waitcnt lgkmcnt(7)
	v_mfma_f32_32x32x16_bf16 v[34:49], v[138:141], v[114:117], v[98:113]
	ds_read_b128 v[138:141], v1 offset:128
	s_waitcnt lgkmcnt(7)
	v_mfma_f32_32x32x16_bf16 v[50:65], v[142:145], v[114:117], v[98:113]
	ds_read_b128 v[142:145], v1 offset:6784
	s_waitcnt lgkmcnt(7)
	v_mfma_f32_32x32x16_bf16 v[34:49], v[146:149], v[118:121], v[34:49]
	ds_read_b128 v[146:149], v1 offset:160
	s_waitcnt lgkmcnt(7)
	v_mfma_f32_32x32x16_bf16 v[50:65], v[150:153], v[118:121], v[50:65]
	ds_read_b128 v[150:153], v1 offset:6816
	s_waitcnt lgkmcnt(7)
	v_mfma_f32_32x32x16_bf16 v[34:49], v[154:157], v[122:125], v[34:49]
	s_waitcnt lgkmcnt(6)
	v_mfma_f32_32x32x16_bf16 v[50:65], v[158:161], v[122:125], v[50:65]
	s_waitcnt lgkmcnt(5)
	v_mfma_f32_32x32x16_bf16 v[34:49], v[162:165], v[126:129], v[34:49]
	s_waitcnt lgkmcnt(4)
	v_mfma_f32_32x32x16_bf16 v[50:65], v[166:169], v[126:129], v[50:65]
	s_waitcnt lgkmcnt(3)
	v_mfma_f32_32x32x16_bf16 v[34:49], v[138:141], v[130:133], v[34:49]
	s_waitcnt lgkmcnt(2)
	v_mfma_f32_32x32x16_bf16 v[50:65], v[142:145], v[130:133], v[50:65]
	s_waitcnt lgkmcnt(1)
	v_mfma_f32_32x32x16_bf16 v[34:49], v[146:149], v[134:137], v[34:49]
	s_waitcnt lgkmcnt(0)
	v_mfma_f32_32x32x16_bf16 v[50:65], v[150:153], v[134:137], v[50:65]
	s_branch .Lat_first_A2

; __device__ __forceinline__ float max3f(float a, float b, float c) { return fmaxf(fmaxf(a, b), c); }
; __device__ __forceinline__ void attn_qk(f32x16& p0, f32x16& p1, const bf16x8 (&kf)[12], const bf16x8 (&qf)[6]) {
;     const f32x16 zero = {0.f, 0.f, 0.f, 0.f, 0.f, 0.f, 0.f, 0.f, 0.f, 0.f, 0.f, 0.f, 0.f, 0.f, 0.f, 0.f};
; #pragma unroll
;     for (int ks = 0; ks < 6; ++ks) {
;         p0 = __builtin_amdgcn_mfma_f32_32x32x16_bf16(kf[2 * ks], qf[ks], ks == 0 ? zero : p0, 0, 0, 0);
;         p1 = __builtin_amdgcn_mfma_f32_32x32x16_bf16(kf[2 * ks + 1], qf[ks], ks == 0 ? zero : p1, 0, 0, 0);
;     }
; __device__ __forceinline__ void attn_softmax(f32x16& p0, f32x16& p1, bf16x8 (&pb)[4], f32x16& o0, f32x16& o1, float& m_run, float& l_run) {
;     float mx = max3f(p0[0], p0[1], p1[0]), my = max3f(p0[2], p0[3], p1[1]);
;     mx = max3f(mx, p1[2], p1[3]);
; #pragma unroll
;     for (int r = 4; r < 16; r += 4) { mx = max3f(mx, p0[r], p0[r + 1]); my = max3f(my, p0[r + 2], p0[r + 3]); mx = max3f(mx, p1[r], p1[r + 1]); my = max3f(my, p1[r + 2], p1[r + 3]); }
;     mx = fmaxf(mx, my);
;     { auto rr = __builtin_amdgcn_permlane32_swap(__float_as_uint(mx), __float_as_uint(mx), false, false); mx = fmaxf(__uint_as_float(rr[0]), __uint_as_float(rr[1])); }
;     const float m_new = fmaxf(m_run, mx);
;     const float alpha = __builtin_amdgcn_exp2f(m_run - m_new);
;     m_run = m_new;
;     p0 = p0 - m_new; p1 = p1 - m_new;
; #pragma unroll
;     for (int r = 0; r < 16; ++r) { p0[r] = __builtin_amdgcn_exp2f(p0[r]); p1[r] = __builtin_amdgcn_exp2f(p1[r]); }
;     f32x16 sm = p0 + p1;
;     f32x2v s2 = (f32x2v){sm[0], sm[1]} + (f32x2v){sm[2], sm[3]};
; #pragma unroll
;     for (int r = 4; r < 16; r += 2) s2 += (f32x2v){sm[r], sm[r + 1]};
;     l_run = l_run * alpha + (s2[0] + s2[1]);
;     o0 = o0 * alpha; o1 = o1 * alpha;
.Lat_resc_B2:
	v_frexp_exp_i32_f32_e32 v250, v1
	v_max_i32_e32 v250, 0, v250
	v_mov_b32_e32 v251, v250
	s_nop 1
	v_permlane32_swap_b32_e32 v250, v251
	v_max_i32_e32 v250, v250, v251
	v_sub_u32_e32 v251, 0, v250
	v_ldexp_f32 v66, v66, v251
	v_ldexp_f32 v67, v67, v251
	v_ldexp_f32 v68, v68, v251
	v_ldexp_f32 v69, v69, v251
	v_ldexp_f32 v70, v70, v251
	v_ldexp_f32 v71, v71, v251
	v_ldexp_f32 v72, v72, v251
	v_ldexp_f32 v73, v73, v251
	v_ldexp_f32 v74, v74, v251
	v_ldexp_f32 v75, v75, v251
	v_ldexp_f32 v76, v76, v251
	v_ldexp_f32 v77, v77, v251
	v_ldexp_f32 v78, v78, v251
	v_ldexp_f32 v79, v79, v251
	v_ldexp_f32 v80, v80, v251
	v_ldexp_f32 v81, v81, v251
	v_ldexp_f32 v82, v82, v251
	v_ldexp_f32 v83, v83, v251
	v_ldexp_f32 v84, v84, v251
	v_ldexp_f32 v85, v85, v251
	v_ldexp_f32 v86, v86, v251
	v_ldexp_f32 v87, v87, v251
	v_ldexp_f32 v88, v88, v251
	v_ldexp_f32 v89, v89, v251
	v_ldexp_f32 v90, v90, v251
	v_ldexp_f32 v91, v91, v251
	v_ldexp_f32 v92, v92, v251
	v_ldexp_f32 v93, v93, v251
	v_ldexp_f32 v94, v94, v251
	v_ldexp_f32 v95, v95, v251
	v_ldexp_f32 v96, v96, v251
	v_ldexp_f32 v97, v97, v251
	v_ldexp_f32 v1, v1, v251
	v_ldexp_f32 v227, v227, v251
	v_ldexp_f32 v2, v2, v251
	v_ldexp_f32 v3, v3, v251
	v_ldexp_f32 v4, v4, v251
	v_ldexp_f32 v5, v5, v251
	v_ldexp_f32 v6, v6, v251
	v_ldexp_f32 v7, v7, v251
	v_ldexp_f32 v8, v8, v251
	v_ldexp_f32 v9, v9, v251
	v_ldexp_f32 v10, v10, v251
	v_ldexp_f32 v11, v11, v251
	v_ldexp_f32 v12, v12, v251
	v_ldexp_f32 v13, v13, v251
	v_ldexp_f32 v14, v14, v251
	v_ldexp_f32 v15, v15, v251
	v_ldexp_f32 v16, v16, v251
	v_ldexp_f32 v17, v17, v251
	v_ldexp_f32 v18, v18, v251
	v_ldexp_f32 v19, v19, v251
	v_ldexp_f32 v20, v20, v251
	v_ldexp_f32 v21, v21, v251
	v_ldexp_f32 v22, v22, v251
	v_ldexp_f32 v23, v23, v251
	v_ldexp_f32 v24, v24, v251
	v_ldexp_f32 v25, v25, v251
	v_ldexp_f32 v26, v26, v251
	v_ldexp_f32 v27, v27, v251
	v_ldexp_f32 v28, v28, v251
	v_ldexp_f32 v29, v29, v251
	v_ldexp_f32 v30, v30, v251
	v_ldexp_f32 v31, v31, v251
	v_ldexp_f32 v32, v32, v251
	v_ldexp_f32 v33, v33, v251
	v_cvt_f32_i32_e32 v252, v250
	v_add_f32_e32 v248, v248, v252
	v_sub_f32_e32 v253, 0, v248
	v_mov_b32_e32 v98, v253
	v_mov_b32_e32 v99, v253
	v_mov_b32_e32 v100, v253
	v_mov_b32_e32 v101, v253
	v_mov_b32_e32 v102, v253
	v_mov_b32_e32 v103, v253
	v_mov_b32_e32 v104, v253
	v_mov_b32_e32 v105, v253
	v_mov_b32_e32 v106, v253
	v_mov_b32_e32 v107, v253
	v_mov_b32_e32 v108, v253
	v_mov_b32_e32 v109, v253
	v_mov_b32_e32 v110, v253
	v_mov_b32_e32 v111, v253
	v_mov_b32_e32 v112, v253
	v_mov_b32_e32 v113, v253
	s_nop 1
	s_branch .Lat_fast_B2
.Lat_redo_B2:
	s_nop 15
	s_mov_b32 s41, 1
	v_add_u32_e32 v1, s37, v222
	ds_read_b128 v[154:157], v1 offset:13312
	ds_read_b128 v[158:161], v1 offset:19968
	ds_read_b128 v[162:165], v1 offset:13344
	ds_read_b128 v[166:169], v1 offset:20000
	ds_read_b128 v[138:141], v1 offset:13376
	ds_read_b128 v[142:145], v1 offset:20032
	ds_read_b128 v[146:149], v1 offset:13408
	ds_read_b128 v[150:153], v1 offset:20064
	s_waitcnt lgkmcnt(7)
	v_mfma_f32_32x32x16_bf16 v[66:81], v[154:157], v[114:117], v[98:113]
	ds_read_b128 v[154:157], v1 offset:13440
	s_waitcnt lgkmcnt(7)
	v_mfma_f32_32x32x16_bf16 v[82:97], v[158:161], v[114:117], v[98:113]
	ds_read_b128 v[158:161], v1 offset:20096
	s_waitcnt lgkmcnt(7)
	v_mfma_f32_32x32x16_bf16 v[66:81], v[162:165], v[118:121], v[66:81]
	ds_read_b128 v[162:165], v1 offset:13472
	s_waitcnt lgkmcnt(7)
	v_mfma_f32_32x32x16_bf16 v[82:97], v[166:169], v[118:121], v[82:97]
	ds_read_b128 v[166:169], v1 offset:20128
	s_waitcnt lgkmcnt(7)
	v_mfma_f32_32x32x16_bf16 v[66:81], v[138:141], v[122:125], v[66:81]
	s_waitcnt lgkmcnt(6)
	v_mfma_f32_32x32x16_bf16 v[82:97], v[142:145], v[122:125], v[82:97]
	s_waitcnt lgkmcnt(5)
	v_mfma_f32_32x32x16_bf16 v[66:81], v[146:149], v[126:129], v[66:81]
	s_waitcnt lgkmcnt(4)
	v_mfma_f32_32x32x16_bf16 v[82:97], v[150:153], v[126:129], v[82:97]
	s_waitcnt lgkmcnt(3)
	v_mfma_f32_32x32x16_bf16 v[66:81], v[154:157], v[130:133], v[66:81]
	s_waitcnt lgkmcnt(2)
	v_mfma_f32_32x32x16_bf16 v[82:97], v[158:161], v[130:133], v[82:97]
	s_waitcnt lgkmcnt(1)
	v_mfma_f32_32x32x16_bf16 v[66:81], v[162:165], v[134:137], v[66:81]
	s_waitcnt lgkmcnt(0)
	v_mfma_f32_32x32x16_bf16 v[82:97], v[166:169], v[134:137], v[82:97]
	s_branch .Lat_first_B2

; __device__ __forceinline__ float max3f(float a, float b, float c) { return fmaxf(fmaxf(a, b), c); }
; __device__ __forceinline__ void attn_softmax(f32x16& p0, f32x16& p1, bf16x8 (&pb)[4], f32x16& o0, f32x16& o1, float& m_run, float& l_run) {
;     float mx = max3f(p0[0], p0[1], p1[0]), my = max3f(p0[2], p0[3], p1[1]);
;     mx = max3f(mx, p1[2], p1[3]);
; #pragma unroll
;     for (int r = 4; r < 16; r += 4) { mx = max3f(mx, p0[r], p0[r + 1]); my = max3f(my, p0[r + 2], p0[r + 3]); mx = max3f(mx, p1[r], p1[r + 1]); my = max3f(my, p1[r + 2], p1[r + 3]); }
;     mx = fmaxf(mx, my);
;     { auto rr = __builtin_amdgcn_permlane32_swap(__float_as_uint(mx), __float_as_uint(mx), false, false); mx = fmaxf(__uint_as_float(rr[0]), __uint_as_float(rr[1])); }
;     const float m_new = fmaxf(m_run, mx);
;     const float alpha = __builtin_amdgcn_exp2f(m_run - m_new);
;     m_run = m_new;
;     p0 = p0 - m_new; p1 = p1 - m_new;
; #pragma unroll
;     for (int r = 0; r < 16; ++r) { p0[r] = __builtin_amdgcn_exp2f(p0[r]); p1[r] = __builtin_amdgcn_exp2f(p1[r]); }
;     f32x16 sm = p0 + p1;
;     f32x2v s2 = (f32x2v){sm[0], sm[1]} + (f32x2v){sm[2], sm[3]};
; #pragma unroll
;     for (int r = 4; r < 16; r += 2) s2 += (f32x2v){sm[r], sm[r + 1]};
;     l_run = l_run * alpha + (s2[0] + s2[1]);
;     o0 = o0 * alpha; o1 = o1 * alpha;
.Lat_resc_A1:
	v_frexp_exp_i32_f32_e32 v250, v1
	v_max_i32_e32 v250, 0, v250
	v_mov_b32_e32 v251, v250
	s_nop 1
	v_permlane32_swap_b32_e32 v250, v251
	v_max_i32_e32 v250, v250, v251
	v_sub_u32_e32 v251, 0, v250
	v_ldexp_f32 v34, v34, v251
	v_ldexp_f32 v35, v35, v251
	v_ldexp_f32 v36, v36, v251
	v_ldexp_f32 v37, v37, v251
	v_ldexp_f32 v38, v38, v251
	v_ldexp_f32 v39, v39, v251
	v_ldexp_f32 v40, v40, v251
	v_ldexp_f32 v41, v41, v251
	v_ldexp_f32 v42, v42, v251
	v_ldexp_f32 v43, v43, v251
	v_ldexp_f32 v44, v44, v251
	v_ldexp_f32 v45, v45, v251
	v_ldexp_f32 v46, v46, v251
	v_ldexp_f32 v47, v47, v251
	v_ldexp_f32 v48, v48, v251
	v_ldexp_f32 v49, v49, v251
	v_ldexp_f32 v50, v50, v251
	v_ldexp_f32 v51, v51, v251
	v_ldexp_f32 v52, v52, v251
	v_ldexp_f32 v53, v53, v251
	v_ldexp_f32 v54, v54, v251
	v_ldexp_f32 v55, v55, v251
	v_ldexp_f32 v56, v56, v251
	v_ldexp_f32 v57, v57, v251
	v_ldexp_f32 v58, v58, v251
	v_ldexp_f32 v59, v59, v251
	v_ldexp_f32 v60, v60, v251
	v_ldexp_f32 v61, v61, v251
	v_ldexp_f32 v62, v62, v251
	v_ldexp_f32 v63, v63, v251
	v_ldexp_f32 v64, v64, v251
	v_ldexp_f32 v65, v65, v251
	v_ldexp_f32 v1, v1, v251
	v_ldexp_f32 v227, v227, v251
	v_ldexp_f32 v2, v2, v251
	v_ldexp_f32 v3, v3, v251
	v_ldexp_f32 v4, v4, v251
	v_ldexp_f32 v5, v5, v251
	v_ldexp_f32 v6, v6, v251
	v_ldexp_f32 v7, v7, v251
	v_ldexp_f32 v8, v8, v251
	v_ldexp_f32 v9, v9, v251
	v_ldexp_f32 v10, v10, v251
	v_ldexp_f32 v11, v11, v251
	v_ldexp_f32 v12, v12, v251
	v_ldexp_f32 v13, v13, v251
	v_ldexp_f32 v14, v14, v251
	v_ldexp_f32 v15, v15, v251
	v_ldexp_f32 v16, v16, v251
	v_ldexp_f32 v17, v17, v251
	v_ldexp_f32 v18, v18, v251
	v_ldexp_f32 v19, v19, v251
	v_ldexp_f32 v20, v20, v251
	v_ldexp_f32 v21, v21, v251
	v_ldexp_f32 v22, v22, v251
	v_ldexp_f32 v23, v23, v251
	v_ldexp_f32 v24, v24, v251
	v_ldexp_f32 v25, v25, v251
	v_ldexp_f32 v26, v26, v251
	v_ldexp_f32 v27, v27, v251
	v_ldexp_f32 v28, v28, v251
	v_ldexp_f32 v29, v29, v251
	v_ldexp_f32 v30, v30, v251
	v_ldexp_f32 v31, v31, v251
	v_ldexp_f32 v32, v32, v251
	v_ldexp_f32 v33, v33, v251
	v_cvt_f32_i32_e32 v252, v250
	v_add_f32_e32 v248, v248, v252
	v_sub_f32_e32 v253, 0, v248
	v_mov_b32_e32 v98, v253
	v_mov_b32_e32 v99, v253
	v_mov_b32_e32 v100, v253
	v_mov_b32_e32 v101, v253
	v_mov_b32_e32 v102, v253
	v_mov_b32_e32 v103, v253
	v_mov_b32_e32 v104, v253
	v_mov_b32_e32 v105, v253
	v_mov_b32_e32 v106, v253
	v_mov_b32_e32 v107, v253
	v_mov_b32_e32 v108, v253
	v_mov_b32_e32 v109, v253
	v_mov_b32_e32 v110, v253
	v_mov_b32_e32 v111, v253
	v_mov_b32_e32 v112, v253
	v_mov_b32_e32 v113, v253
	s_nop 1
	s_branch .Lat_fast_A1

; __device__ __forceinline__ void attn_softmax(f32x16& p0, f32x16& p1, bf16x8 (&pb)[4], f32x16& o0, f32x16& o1, float& m_run, float& l_run) {
;     ...
;     const float m_new = fmaxf(m_run, mx);
;     const float alpha = __builtin_amdgcn_exp2f(m_run - m_new);
;     m_run = m_new;
;     p0 = p0 - m_new; p1 = p1 - m_new;
.Lat_fix_B:
	s_nop 15
	s_mov_b32 s6, 0
	v_sub_f32_e32 v66, v66, v218
	v_sub_f32_e32 v67, v67, v218
	v_sub_f32_e32 v68, v68, v218
	v_sub_f32_e32 v69, v69, v218
	v_sub_f32_e32 v70, v70, v218
	v_sub_f32_e32 v71, v71, v218
	v_sub_f32_e32 v72, v72, v218
	v_sub_f32_e32 v73, v73, v218
	v_sub_f32_e32 v74, v74, v218
	v_sub_f32_e32 v75, v75, v218
	v_sub_f32_e32 v76, v76, v218
	v_sub_f32_e32 v77, v77, v218
	v_sub_f32_e32 v78, v78, v218
	v_sub_f32_e32 v79, v79, v218
	v_sub_f32_e32 v80, v80, v218
	v_sub_f32_e32 v81, v81, v218
	v_sub_f32_e32 v82, v82, v218
	v_sub_f32_e32 v83, v83, v218
	v_sub_f32_e32 v84, v84, v218
	v_sub_f32_e32 v85, v85, v218
	v_sub_f32_e32 v86, v86, v218
	v_sub_f32_e32 v87, v87, v218
	v_sub_f32_e32 v88, v88, v218
	v_sub_f32_e32 v89, v89, v218
	v_sub_f32_e32 v90, v90, v218
	v_sub_f32_e32 v91, v91, v218
	v_sub_f32_e32 v92, v92, v218
	v_sub_f32_e32 v93, v93, v218
	v_sub_f32_e32 v94, v94, v218
	v_sub_f32_e32 v95, v95, v218
	v_sub_f32_e32 v96, v96, v218
	v_sub_f32_e32 v97, v97, v218
	v_mov_b32_e32 v218, 0
	s_branch .Lat_fixed_B
